# P10 epilogue: the 32 bf16 residual loads issued up front (counted vmcnt waits) instead of one load + full drain per 16-byte store
# baseline (speedup 1.0000x reference)
.LBB0_1508:
	v_lshl_add_u32 v144, s28, 8, v146
	v_lshl_or_b32 v142, s53, 8, v148
	v_ashrrev_i32_e32 v145, 31, v144
	v_ashrrev_i32_e32 v143, 31, v142
	v_lshlrev_b64 v[140:141], 11, v[144:145]
	v_lshl_add_u64 v[140:141], v[140:141], 0, v[142:143]
	v_lshl_add_u64 v[152:153], v[140:141], 1, s[4:5]
	global_load_dwordx2 v[154:155], v[152:153], off
	s_mov_b32 s90, 0x10000
	s_mov_b32 s91, 0
	s_mov_b32 s92, 0x80000
	s_mov_b32 s93, 0
	v_lshl_add_u64 v[224:225], v[152:153], 0, s[90:91]
	v_lshl_add_u64 v[226:227], v[224:225], 0, s[90:91]
	v_lshl_add_u64 v[228:229], v[226:227], 0, s[90:91]
	v_lshl_add_u64 v[230:231], v[152:153], 0, s[92:93]
	v_lshl_add_u64 v[232:233], v[230:231], 0, s[90:91]
	v_lshl_add_u64 v[234:235], v[232:233], 0, s[90:91]
	v_lshl_add_u64 v[236:237], v[234:235], 0, s[90:91]
	global_load_dwordx2 v[162:163], v[152:153], off offset:32
	global_load_dwordx2 v[164:165], v[152:153], off offset:256
	global_load_dwordx2 v[166:167], v[152:153], off offset:288
	global_load_dwordx2 v[168:169], v[224:225], off
	global_load_dwordx2 v[170:171], v[224:225], off offset:32
	global_load_dwordx2 v[172:173], v[224:225], off offset:256
	global_load_dwordx2 v[174:175], v[224:225], off offset:288
	global_load_dwordx2 v[176:177], v[226:227], off
	global_load_dwordx2 v[178:179], v[226:227], off offset:32
	global_load_dwordx2 v[180:181], v[226:227], off offset:256
	global_load_dwordx2 v[182:183], v[226:227], off offset:288
	global_load_dwordx2 v[184:185], v[228:229], off
	global_load_dwordx2 v[186:187], v[228:229], off offset:32
	global_load_dwordx2 v[188:189], v[228:229], off offset:256
	global_load_dwordx2 v[190:191], v[228:229], off offset:288
	global_load_dwordx2 v[192:193], v[230:231], off
	global_load_dwordx2 v[194:195], v[230:231], off offset:32
	global_load_dwordx2 v[196:197], v[230:231], off offset:256
	global_load_dwordx2 v[198:199], v[230:231], off offset:288
	global_load_dwordx2 v[200:201], v[232:233], off
	global_load_dwordx2 v[202:203], v[232:233], off offset:32
	global_load_dwordx2 v[204:205], v[232:233], off offset:256
	global_load_dwordx2 v[206:207], v[232:233], off offset:288
	global_load_dwordx2 v[208:209], v[234:235], off
	global_load_dwordx2 v[210:211], v[234:235], off offset:32
	global_load_dwordx2 v[212:213], v[234:235], off offset:256
	global_load_dwordx2 v[214:215], v[234:235], off offset:288
	global_load_dwordx2 v[216:217], v[236:237], off
	global_load_dwordx2 v[218:219], v[236:237], off offset:32
	global_load_dwordx2 v[220:221], v[236:237], off offset:256
	global_load_dwordx2 v[222:223], v[236:237], off offset:288
	v_lshl_add_u64 v[156:157], v[140:141], 2, s[82:83]
	s_andn2_b64 vcc, exec, s[0:1]
	s_mov_b64 s[0:1], -1
	s_waitcnt vmcnt(31)
	v_lshlrev_b32_e32 v158, 16, v154
	v_and_b32_e32 v159, 0xffff0000, v154
	v_lshlrev_b32_e32 v154, 16, v155
	v_and_b32_e32 v155, 0xffff0000, v155
	v_pk_add_f32 v[126:127], v[126:127], v[154:155]
	v_pk_add_f32 v[124:125], v[124:125], v[158:159]
	global_store_dwordx4 v[156:157], v[124:127], off sc0 sc1 nt
	s_nop 1
	s_waitcnt vmcnt(31)
	v_mov_b32_e32 v124, v162
	v_mov_b32_e32 v125, v163
	v_lshlrev_b32_e32 v126, 16, v124
	v_and_b32_e32 v127, 0xffff0000, v124
	v_lshlrev_b32_e32 v124, 16, v125
	v_and_b32_e32 v125, 0xffff0000, v125
	v_pk_add_f32 v[122:123], v[122:123], v[124:125]
	v_pk_add_f32 v[120:121], v[120:121], v[126:127]
	global_store_dwordx4 v[156:157], v[120:123], off offset:64 sc0 sc1 nt
	s_nop 1
	s_waitcnt vmcnt(31)
	v_mov_b32_e32 v120, v164
	v_mov_b32_e32 v121, v165
	v_lshlrev_b32_e32 v122, 16, v120
	v_and_b32_e32 v123, 0xffff0000, v120
	v_lshlrev_b32_e32 v120, 16, v121
	v_and_b32_e32 v121, 0xffff0000, v121
	v_pk_add_f32 v[118:119], v[118:119], v[120:121]
	v_pk_add_f32 v[116:117], v[116:117], v[122:123]
	global_store_dwordx4 v[156:157], v[116:119], off offset:512 sc0 sc1 nt
	s_nop 1
	s_waitcnt vmcnt(31)
	v_mov_b32_e32 v116, v166
	v_mov_b32_e32 v117, v167
	v_lshlrev_b32_e32 v122, 16, v116
	v_or_b32_e32 v118, 16, v144
	v_ashrrev_i32_e32 v119, 31, v118
	v_lshlrev_b64 v[118:119], 11, v[118:119]
	v_and_b32_e32 v123, 0xffff0000, v116
	v_lshlrev_b32_e32 v116, 16, v117
	v_and_b32_e32 v117, 0xffff0000, v117
	v_lshl_add_u64 v[118:119], v[118:119], 0, v[142:143]
	v_pk_add_f32 v[110:111], v[110:111], v[116:117]
	v_pk_add_f32 v[108:109], v[108:109], v[122:123]
	v_lshl_add_u64 v[120:121], v[118:119], 1, s[4:5]
	global_store_dwordx4 v[156:157], v[108:111], off offset:576 sc0 sc1 nt
	s_nop 1
	v_lshl_add_u64 v[116:117], v[118:119], 2, s[82:83]
	s_waitcnt vmcnt(31)
	v_mov_b32_e32 v108, v168
	v_mov_b32_e32 v109, v169
	v_lshlrev_b32_e32 v118, 16, v108
	v_and_b32_e32 v119, 0xffff0000, v108
	v_lshlrev_b32_e32 v108, 16, v109
	v_and_b32_e32 v109, 0xffff0000, v109
	v_pk_add_f32 v[110:111], v[114:115], v[108:109]
	v_pk_add_f32 v[108:109], v[112:113], v[118:119]
	global_store_dwordx4 v[116:117], v[108:111], off sc0 sc1 nt
	s_nop 1
	s_waitcnt vmcnt(31)
	v_mov_b32_e32 v108, v170
	v_mov_b32_e32 v109, v171
	v_lshlrev_b32_e32 v110, 16, v108
	v_and_b32_e32 v111, 0xffff0000, v108
	v_lshlrev_b32_e32 v108, 16, v109
	v_and_b32_e32 v109, 0xffff0000, v109
	v_pk_add_f32 v[106:107], v[106:107], v[108:109]
	v_pk_add_f32 v[104:105], v[104:105], v[110:111]
	global_store_dwordx4 v[116:117], v[104:107], off offset:64 sc0 sc1 nt
	s_nop 1
	s_waitcnt vmcnt(31)
	v_mov_b32_e32 v104, v172
	v_mov_b32_e32 v105, v173
	v_lshlrev_b32_e32 v106, 16, v104
	v_and_b32_e32 v107, 0xffff0000, v104
	v_lshlrev_b32_e32 v104, 16, v105
	v_and_b32_e32 v105, 0xffff0000, v105
	v_pk_add_f32 v[102:103], v[102:103], v[104:105]
	v_pk_add_f32 v[100:101], v[100:101], v[106:107]
	global_store_dwordx4 v[116:117], v[100:103], off offset:512 sc0 sc1 nt
	s_nop 1
	s_waitcnt vmcnt(31)
	v_mov_b32_e32 v100, v174
	v_mov_b32_e32 v101, v175
	v_lshlrev_b32_e32 v106, 16, v100
	v_or_b32_e32 v102, 32, v144
	v_ashrrev_i32_e32 v103, 31, v102
	v_lshlrev_b64 v[102:103], 11, v[102:103]
	v_and_b32_e32 v107, 0xffff0000, v100
	v_lshlrev_b32_e32 v100, 16, v101
	v_and_b32_e32 v101, 0xffff0000, v101
	v_lshl_add_u64 v[102:103], v[102:103], 0, v[142:143]
	v_pk_add_f32 v[94:95], v[94:95], v[100:101]
	v_pk_add_f32 v[92:93], v[92:93], v[106:107]
	v_lshl_add_u64 v[104:105], v[102:103], 1, s[4:5]
	global_store_dwordx4 v[116:117], v[92:95], off offset:576 sc0 sc1 nt
	s_nop 1
	v_lshl_add_u64 v[100:101], v[102:103], 2, s[82:83]
	s_waitcnt vmcnt(31)
	v_mov_b32_e32 v92, v176
	v_mov_b32_e32 v93, v177
	v_lshlrev_b32_e32 v102, 16, v92
	v_and_b32_e32 v103, 0xffff0000, v92
	v_lshlrev_b32_e32 v92, 16, v93
	v_and_b32_e32 v93, 0xffff0000, v93
	v_pk_add_f32 v[94:95], v[98:99], v[92:93]
	v_pk_add_f32 v[92:93], v[96:97], v[102:103]
	global_store_dwordx4 v[100:101], v[92:95], off sc0 sc1 nt
	s_nop 1
	s_waitcnt vmcnt(31)
	v_mov_b32_e32 v92, v178
	v_mov_b32_e32 v93, v179
	v_lshlrev_b32_e32 v94, 16, v92
	v_and_b32_e32 v95, 0xffff0000, v92
	v_lshlrev_b32_e32 v92, 16, v93
	v_and_b32_e32 v93, 0xffff0000, v93
	v_pk_add_f32 v[90:91], v[90:91], v[92:93]
	v_pk_add_f32 v[88:89], v[88:89], v[94:95]
	global_store_dwordx4 v[100:101], v[88:91], off offset:64 sc0 sc1 nt
	s_nop 1
	s_waitcnt vmcnt(31)
	v_mov_b32_e32 v88, v180
	v_mov_b32_e32 v89, v181
	v_lshlrev_b32_e32 v90, 16, v88
	v_and_b32_e32 v91, 0xffff0000, v88
	v_lshlrev_b32_e32 v88, 16, v89
	v_and_b32_e32 v89, 0xffff0000, v89
	v_pk_add_f32 v[86:87], v[86:87], v[88:89]
	v_pk_add_f32 v[84:85], v[84:85], v[90:91]
	global_store_dwordx4 v[100:101], v[84:87], off offset:512 sc0 sc1 nt
	s_nop 1
	s_waitcnt vmcnt(31)
	v_mov_b32_e32 v84, v182
	v_mov_b32_e32 v85, v183
	v_lshlrev_b32_e32 v90, 16, v84
	v_or_b32_e32 v86, 48, v144
	v_ashrrev_i32_e32 v87, 31, v86
	v_lshlrev_b64 v[86:87], 11, v[86:87]
	v_and_b32_e32 v91, 0xffff0000, v84
	v_lshlrev_b32_e32 v84, 16, v85
	v_and_b32_e32 v85, 0xffff0000, v85
	v_lshl_add_u64 v[86:87], v[86:87], 0, v[142:143]
	v_pk_add_f32 v[78:79], v[78:79], v[84:85]
	v_pk_add_f32 v[76:77], v[76:77], v[90:91]
	v_lshl_add_u64 v[88:89], v[86:87], 1, s[4:5]
	global_store_dwordx4 v[100:101], v[76:79], off offset:576 sc0 sc1 nt
	s_nop 1
	v_lshl_add_u64 v[84:85], v[86:87], 2, s[82:83]
	s_waitcnt vmcnt(31)
	v_mov_b32_e32 v76, v184
	v_mov_b32_e32 v77, v185
	v_lshlrev_b32_e32 v86, 16, v76
	v_and_b32_e32 v87, 0xffff0000, v76
	v_lshlrev_b32_e32 v76, 16, v77
	v_and_b32_e32 v77, 0xffff0000, v77
	v_pk_add_f32 v[78:79], v[82:83], v[76:77]
	v_pk_add_f32 v[76:77], v[80:81], v[86:87]
	global_store_dwordx4 v[84:85], v[76:79], off sc0 sc1 nt
	s_nop 1
	s_waitcnt vmcnt(31)
	v_mov_b32_e32 v76, v186
	v_mov_b32_e32 v77, v187
	v_lshlrev_b32_e32 v78, 16, v76
	v_and_b32_e32 v79, 0xffff0000, v76
	v_lshlrev_b32_e32 v76, 16, v77
	v_and_b32_e32 v77, 0xffff0000, v77
	v_pk_add_f32 v[74:75], v[74:75], v[76:77]
	v_pk_add_f32 v[72:73], v[72:73], v[78:79]
	global_store_dwordx4 v[84:85], v[72:75], off offset:64 sc0 sc1 nt
	s_nop 1
	s_waitcnt vmcnt(31)
	v_mov_b32_e32 v72, v188
	v_mov_b32_e32 v73, v189
	v_lshlrev_b32_e32 v74, 16, v72
	v_and_b32_e32 v75, 0xffff0000, v72
	v_lshlrev_b32_e32 v72, 16, v73
	v_and_b32_e32 v73, 0xffff0000, v73
	v_pk_add_f32 v[70:71], v[70:71], v[72:73]
	v_pk_add_f32 v[68:69], v[68:69], v[74:75]
	global_store_dwordx4 v[84:85], v[68:71], off offset:512 sc0 sc1 nt
	s_nop 1
	s_waitcnt vmcnt(31)
	v_mov_b32_e32 v68, v190
	v_mov_b32_e32 v69, v191
	v_lshlrev_b32_e32 v74, 16, v68
	v_and_b32_e32 v75, 0xffff0000, v68
	v_lshlrev_b32_e32 v68, 16, v69
	v_and_b32_e32 v69, 0xffff0000, v69
	v_lshl_add_u64 v[70:71], v[140:141], 0, s[10:11]
	v_pk_add_f32 v[66:67], v[66:67], v[68:69]
	v_pk_add_f32 v[64:65], v[64:65], v[74:75]
	v_lshl_add_u64 v[72:73], v[70:71], 1, s[4:5]
	global_store_dwordx4 v[84:85], v[64:67], off offset:576 sc0 sc1 nt
	s_nop 1
	s_waitcnt vmcnt(31)
	v_mov_b32_e32 v64, v192
	v_mov_b32_e32 v65, v193
	v_lshlrev_b32_e32 v68, 16, v64
	v_and_b32_e32 v69, 0xffff0000, v64
	v_lshlrev_b32_e32 v64, 16, v65
	v_and_b32_e32 v65, 0xffff0000, v65
	v_lshl_add_u64 v[66:67], v[70:71], 2, s[82:83]
	v_pk_add_f32 v[62:63], v[62:63], v[64:65]
	v_pk_add_f32 v[60:61], v[60:61], v[68:69]
	global_store_dwordx4 v[66:67], v[60:63], off sc0 sc1 nt
	s_nop 1
	s_waitcnt vmcnt(31)
	v_mov_b32_e32 v60, v194
	v_mov_b32_e32 v61, v195
	v_lshlrev_b32_e32 v62, 16, v60
	v_and_b32_e32 v63, 0xffff0000, v60
	v_lshlrev_b32_e32 v60, 16, v61
	v_and_b32_e32 v61, 0xffff0000, v61
	v_pk_add_f32 v[58:59], v[58:59], v[60:61]
	v_pk_add_f32 v[56:57], v[56:57], v[62:63]
	global_store_dwordx4 v[66:67], v[56:59], off offset:64 sc0 sc1 nt
	s_nop 1
	s_waitcnt vmcnt(31)
	v_mov_b32_e32 v56, v196
	v_mov_b32_e32 v57, v197
	v_lshlrev_b32_e32 v58, 16, v56
	v_and_b32_e32 v59, 0xffff0000, v56
	v_lshlrev_b32_e32 v56, 16, v57
	v_and_b32_e32 v57, 0xffff0000, v57
	v_pk_add_f32 v[54:55], v[54:55], v[56:57]
	v_pk_add_f32 v[52:53], v[52:53], v[58:59]
	global_store_dwordx4 v[66:67], v[52:55], off offset:512 sc0 sc1 nt
	s_nop 1
	s_waitcnt vmcnt(31)
	v_mov_b32_e32 v52, v198
	v_mov_b32_e32 v53, v199
	v_lshlrev_b32_e32 v58, 16, v52
	v_and_b32_e32 v59, 0xffff0000, v52
	v_lshlrev_b32_e32 v52, 16, v53
	v_and_b32_e32 v53, 0xffff0000, v53
	v_lshl_add_u64 v[54:55], v[140:141], 0, s[12:13]
	v_pk_add_f32 v[46:47], v[46:47], v[52:53]
	v_pk_add_f32 v[44:45], v[44:45], v[58:59]
	v_lshl_add_u64 v[56:57], v[54:55], 1, s[4:5]
	global_store_dwordx4 v[66:67], v[44:47], off offset:576 sc0 sc1 nt
	s_nop 1
	v_lshl_add_u64 v[52:53], v[54:55], 2, s[82:83]
	s_waitcnt vmcnt(31)
	v_mov_b32_e32 v44, v200
	v_mov_b32_e32 v45, v201
	v_lshlrev_b32_e32 v54, 16, v44
	v_and_b32_e32 v55, 0xffff0000, v44
	v_lshlrev_b32_e32 v44, 16, v45
	v_and_b32_e32 v45, 0xffff0000, v45
	v_pk_add_f32 v[46:47], v[50:51], v[44:45]
	v_pk_add_f32 v[44:45], v[48:49], v[54:55]
	global_store_dwordx4 v[52:53], v[44:47], off sc0 sc1 nt
	s_nop 1
	s_waitcnt vmcnt(31)
	v_mov_b32_e32 v44, v202
	v_mov_b32_e32 v45, v203
	v_lshlrev_b32_e32 v46, 16, v44
	v_and_b32_e32 v47, 0xffff0000, v44
	v_lshlrev_b32_e32 v44, 16, v45
	v_and_b32_e32 v45, 0xffff0000, v45
	v_pk_add_f32 v[42:43], v[42:43], v[44:45]
	v_pk_add_f32 v[40:41], v[40:41], v[46:47]
	global_store_dwordx4 v[52:53], v[40:43], off offset:64 sc0 sc1 nt
	s_nop 1
	s_waitcnt vmcnt(31)
	v_mov_b32_e32 v40, v204
	v_mov_b32_e32 v41, v205
	v_lshlrev_b32_e32 v42, 16, v40
	v_and_b32_e32 v43, 0xffff0000, v40
	v_lshlrev_b32_e32 v40, 16, v41
	v_and_b32_e32 v41, 0xffff0000, v41
	v_pk_add_f32 v[38:39], v[38:39], v[40:41]
	v_pk_add_f32 v[36:37], v[36:37], v[42:43]
	global_store_dwordx4 v[52:53], v[36:39], off offset:512 sc0 sc1 nt
	s_nop 1
	s_waitcnt vmcnt(31)
	v_mov_b32_e32 v36, v206
	v_mov_b32_e32 v37, v207
	v_lshlrev_b32_e32 v42, 16, v36
	v_and_b32_e32 v43, 0xffff0000, v36
	v_lshlrev_b32_e32 v36, 16, v37
	v_and_b32_e32 v37, 0xffff0000, v37
	v_lshl_add_u64 v[38:39], v[140:141], 0, s[14:15]
	v_pk_add_f32 v[30:31], v[30:31], v[36:37]
	v_pk_add_f32 v[28:29], v[28:29], v[42:43]
	v_lshl_add_u64 v[40:41], v[38:39], 1, s[4:5]
	global_store_dwordx4 v[52:53], v[28:31], off offset:576 sc0 sc1 nt
	s_nop 1
	v_lshl_add_u64 v[36:37], v[38:39], 2, s[82:83]
	s_waitcnt vmcnt(31)
	v_mov_b32_e32 v28, v208
	v_mov_b32_e32 v29, v209
	v_lshlrev_b32_e32 v38, 16, v28
	v_and_b32_e32 v39, 0xffff0000, v28
	v_lshlrev_b32_e32 v28, 16, v29
	v_and_b32_e32 v29, 0xffff0000, v29
	v_pk_add_f32 v[30:31], v[34:35], v[28:29]
	v_pk_add_f32 v[28:29], v[32:33], v[38:39]
	global_store_dwordx4 v[36:37], v[28:31], off sc0 sc1 nt
	s_nop 1
	s_waitcnt vmcnt(31)
	v_mov_b32_e32 v28, v210
	v_mov_b32_e32 v29, v211
	v_lshlrev_b32_e32 v30, 16, v28
	v_and_b32_e32 v31, 0xffff0000, v28
	v_lshlrev_b32_e32 v28, 16, v29
	v_and_b32_e32 v29, 0xffff0000, v29
	v_pk_add_f32 v[26:27], v[26:27], v[28:29]
	v_pk_add_f32 v[24:25], v[24:25], v[30:31]
	global_store_dwordx4 v[36:37], v[24:27], off offset:64 sc0 sc1 nt
	s_nop 1
	s_waitcnt vmcnt(31)
	v_mov_b32_e32 v24, v212
	v_mov_b32_e32 v25, v213
	v_lshlrev_b32_e32 v26, 16, v24
	v_and_b32_e32 v27, 0xffff0000, v24
	v_lshlrev_b32_e32 v24, 16, v25
	v_and_b32_e32 v25, 0xffff0000, v25
	v_pk_add_f32 v[22:23], v[22:23], v[24:25]
	v_pk_add_f32 v[20:21], v[20:21], v[26:27]
	global_store_dwordx4 v[36:37], v[20:23], off offset:512 sc0 sc1 nt
	s_nop 1
	s_waitcnt vmcnt(31)
	v_mov_b32_e32 v20, v214
	v_mov_b32_e32 v21, v215
	v_lshlrev_b32_e32 v26, 16, v20
	v_and_b32_e32 v27, 0xffff0000, v20
	v_lshlrev_b32_e32 v20, 16, v21
	v_and_b32_e32 v21, 0xffff0000, v21
	v_lshl_add_u64 v[22:23], v[140:141], 0, s[16:17]
	v_pk_add_f32 v[14:15], v[14:15], v[20:21]
	v_pk_add_f32 v[12:13], v[12:13], v[26:27]
	v_lshl_add_u64 v[24:25], v[22:23], 1, s[4:5]
	global_store_dwordx4 v[36:37], v[12:15], off offset:576 sc0 sc1 nt
	s_nop 1
	v_lshl_add_u64 v[20:21], v[22:23], 2, s[82:83]
	s_waitcnt vmcnt(31)
	v_mov_b32_e32 v12, v216
	v_mov_b32_e32 v13, v217
	v_lshlrev_b32_e32 v22, 16, v12
	v_and_b32_e32 v23, 0xffff0000, v12
	v_lshlrev_b32_e32 v12, 16, v13
	v_and_b32_e32 v13, 0xffff0000, v13
	v_pk_add_f32 v[14:15], v[18:19], v[12:13]
	v_pk_add_f32 v[12:13], v[16:17], v[22:23]
	global_store_dwordx4 v[20:21], v[12:15], off sc0 sc1 nt
	s_nop 1
	s_waitcnt vmcnt(31)
	v_mov_b32_e32 v12, v218
	v_mov_b32_e32 v13, v219
	v_lshlrev_b32_e32 v14, 16, v12
	v_and_b32_e32 v15, 0xffff0000, v12
	v_lshlrev_b32_e32 v12, 16, v13
	v_and_b32_e32 v13, 0xffff0000, v13
	v_pk_add_f32 v[10:11], v[10:11], v[12:13]
	v_pk_add_f32 v[8:9], v[8:9], v[14:15]
	global_store_dwordx4 v[20:21], v[8:11], off offset:64 sc0 sc1 nt
	s_nop 1
	s_waitcnt vmcnt(31)
	v_mov_b32_e32 v8, v220
	v_mov_b32_e32 v9, v221
	v_lshlrev_b32_e32 v10, 16, v8
	v_and_b32_e32 v11, 0xffff0000, v8
	v_lshlrev_b32_e32 v8, 16, v9
	v_and_b32_e32 v9, 0xffff0000, v9
	v_pk_add_f32 v[6:7], v[6:7], v[8:9]
	v_pk_add_f32 v[4:5], v[4:5], v[10:11]
	global_store_dwordx4 v[20:21], v[4:7], off offset:512 sc0 sc1 nt
	s_nop 1
	s_waitcnt vmcnt(31)
	v_mov_b32_e32 v4, v222
	v_mov_b32_e32 v5, v223
	v_lshlrev_b32_e32 v6, 16, v4
	v_and_b32_e32 v7, 0xffff0000, v4
	v_lshlrev_b32_e32 v4, 16, v5
	v_and_b32_e32 v5, 0xffff0000, v5
	v_pk_add_f32 v[2:3], v[2:3], v[4:5]
	v_pk_add_f32 v[0:1], v[0:1], v[6:7]
	global_store_dwordx4 v[20:21], v[0:3], off offset:576 sc0 sc1 nt
	s_cbranch_vccnz .LBB0_1497
	s_andn2_b64 vcc, exec, s[2:3]
	s_cbranch_vccnz .LBB0_1496
	s_barrier
	s_branch .LBB0_1496
